# f1->ln->f3->ple seams use XCD-local barriers (no L2 write-back, no cross-XCC step) when the census shows XCC == blockIdx&7 for every workgroup; rows phases XCD-aligned
# speedup vs baseline: 1.0057x; 1.0057x over previous
; DI int half_() { return __builtin_amdgcn_readfirstlane((int)(threadIdx.x >> 8)); }
; __global__ void __launch_bounds__(512, 2) mega(Params p_unused, int ph0, int ph1) {
;   __shared__ __attribute__((aligned(16))) unsigned char lds_all[LDS_BYTES];
;   unsigned char* ldsb = lds_all + half_() * LDS_HALF;
;   cg::grid_group grid = cg::this_grid();
;   for (int ph = ph0; ph < ph1; ++ph) {
;     const __attribute__((address_space(4))) Params* pp = (const __attribute__((address_space(4))) Params*)__builtin_amdgcn_kernarg_segment_ptr();
;     asm volatile("" : "+s"(pp));
;     PREF p = *pp;
;     if (ph1 < 0) grid.sync();
;     if (ph > ph0) grid_barrier(p.bar, (unsigned)(ph - ph0));
.LBB0_1:
	s_lshr_b32 s33, s0, 8
	v_readlane_b32 s0, v254, 1
	v_readlane_b32 s1, v254, 2
	s_add_u32 s2, s0, 0x1a8
	s_addc_u32 s3, s1, 0
	v_writelane_b32 v254, s2, 5
	v_lshrrev_b32_e32 v1, 20, v0
	v_lshrrev_b32_e32 v0, 10, v0
	v_writelane_b32 v254, s3, 6
	v_or_b32_e32 v0, v0, v1
	s_movk_i32 s2, 0x3ff
	v_and_or_b32 v0, v0, s2, v168
	v_readlane_b32 s8, v254, 3
	v_cmp_eq_u32_e64 s[2:3], 0, v0
	v_readlane_b32 s9, v254, 4
	s_load_dword s5, s[0:1], 0x1a8
	v_writelane_b32 v254, s2, 7
	s_cmp_lt_i32 s9, 0
	s_cselect_b64 s[0:1], -1, 0
	v_writelane_b32 v254, s3, 8
	v_cmp_eq_u32_e64 s[2:3], 0, v168
	s_waitcnt lgkmcnt(0)
	s_lshr_b32 s45, s5, 3
	s_mul_i32 s33, s33, 0x12400
	v_writelane_b32 v254, s2, 9
	v_cndmask_b32_e64 v0, 0, 1, s[0:1]
	v_cmp_ne_u32_e64 s[0:1], 1, v0
	v_writelane_b32 v254, s3, 10
	v_mbcnt_lo_u32_b32 v0, -1, 0
	v_readlane_b32 s4, v254, 0
	s_and_b32 s2, s4, 15
	s_xor_b32 s3, s2, 15
	s_add_i32 s3, s5, s3
	s_lshr_b32 s3, s3, 4
	s_lshl_b32 s2, s2, 6
	s_lshr_b32 s46, s4, 3
	s_cmpk_lt_u32 s4, 0x200
	v_writelane_b32 v254, s3, 11
	s_cselect_b64 s[6:7], -1, 0
	s_lshl_b32 s3, s4, 4
	s_and_b32 s47, s3, 0x70
	s_lshl_b32 s3, s4, 3
	s_lshl_b32 s48, s5, 3
	v_writelane_b32 v254, s6, 12
	s_cmpk_lt_i32 s4, 0x100
	s_mov_b32 s53, 0
	v_writelane_b32 v254, s7, 13
	s_cselect_b64 s[6:7], -1, 0
	v_writelane_b32 v254, s6, 14
	s_ashr_i32 s49, s48, 31
	s_lshl_b32 s64, s5, 9
	v_writelane_b32 v254, s7, 15
	s_add_i32 s6, s33, 0x12000
	v_writelane_b32 v254, s6, 16
	s_lshl_b32 s6, s4, 9
	v_writelane_b32 v254, s6, 17
	s_lshl_b64 s[6:7], s[48:49], 11
	v_writelane_b32 v254, s6, 18
	s_ashr_i32 s65, s64, 31
	s_lshl_b32 s70, s4, 1
	v_writelane_b32 v254, s7, 19
	v_writelane_b32 v254, s3, 20
	s_addk_i32 s3, 0x4000
	v_writelane_b32 v254, s3, 21
	s_lshl_b32 s3, s4, 8
	v_writelane_b32 v254, s3, 22
	s_lshl_b32 s3, s5, 8
	v_writelane_b32 v254, s3, 23
	s_add_i32 s3, s33, 0x4000
	v_writelane_b32 v254, s3, 24
	s_lshl_b32 s3, s4, 6
	v_writelane_b32 v254, s3, 25
	s_lshl_b64 s[6:7], s[64:65], 4
	v_writelane_b32 v254, s6, 26
	s_lshl_b32 s3, s5, 10
	s_lshl_b32 s71, s5, 1
	v_writelane_b32 v254, s7, 27
	s_lshl_b64 s[6:7], s[64:65], 5
	v_writelane_b32 v254, s6, 28
	s_lshl_b32 s81, s4, 7
	s_lshl_b32 s84, s5, 7
	v_writelane_b32 v254, s7, 29
	s_lshl_b64 s[6:7], s[48:49], 12
	v_writelane_b32 v254, s6, 30
	s_lshl_b32 s85, s5, 6
	s_movk_i32 s66, 0x200
	v_writelane_b32 v254, s7, 31
	v_writelane_b32 v254, s5, 32
	v_writelane_b32 v254, s3, 33
	s_lshl_b64 s[4:5], s[64:65], 2
	v_writelane_b32 v254, s4, 34
	v_and_b32_e32 v169, 0xff, v168
	s_movk_i32 s67, 0x100
	v_writelane_b32 v254, s5, 35
	v_writelane_b32 v254, s0, 36
	s_lshl_b64 s[72:73], s[64:65], 6
	v_mov_b32_e32 v1, 0
	v_writelane_b32 v254, s1, 37
	s_lshl_b32 s0, s2, 2
	v_writelane_b32 v254, s0, 38
	v_writelane_b32 v254, s45, 39
	v_writelane_b32 v254, s46, 40
	v_writelane_b32 v254, s47, 41
	s_mov_b32 s0, s48
	v_writelane_b32 v254, s0, 42
	s_mov_b32 s88, 0x10000
	v_mov_b32_e32 v170, 0x1000
	v_writelane_b32 v254, s1, 43
	s_mov_b32 s0, s64
	s_mov_b64 s[76:77], 0x80
	s_mov_b64 s[78:79], 0x40080
	s_mov_b64 s[42:43], 0x12b0100
	s_mov_b64 s[82:83], 0x100
	s_mov_b64 s[86:87], 0x40100
	s_mov_b64 s[90:91], 0x180
	s_movk_i32 s89, 0x180
	s_movk_i32 s92, 0x210
	s_movk_i32 s93, 0x80
	v_mov_b32_e32 v171, 0x3727c5ac
	s_mov_b32 s61, 0x800000
	s_movk_i32 s80, 0x1000
	s_mov_b64 s[50:51], 0x580100
	s_mov_b64 s[38:39], 0x980100
	s_mov_b64 s[4:5], 0x580180
	s_mov_b64 s[74:75], 0x980180
	s_movk_i32 s60, 0x1540
	s_movk_i32 s96, 0x300
	s_movk_i32 s97, 0x90
	s_mov_b32 s94, 0xff800000
	v_mbcnt_hi_u32_b32 v172, -1, v0
	v_mov_b32_e32 v163, 1.0
	s_mov_b64 s[2:3], 0xaa000
	v_mov_b32_e32 v173, 0x358637bd
	s_movk_i32 s95, 0x400
	s_mov_b64 s[6:7], 0x40180
	s_movk_i32 s58, 0xaa0
	s_movk_i32 s59, 0x600
	s_movk_i32 s54, 0x2a80
	v_mov_b32_e32 v174, 0x3c0881c4
	v_mov_b32_e32 v175, 0xbab64f3b
	v_mov_b32_e32 v176, 0xff800000
	v_mov_b32_e32 v177, 0x7f800000
	v_not_b32_e32 v178, 63
	v_not_b32_e32 v179, 31
	v_mov_b32_e32 v180, 0x7fc00000
	v_mov_b32_e32 v181, 0x37000000
	s_mov_b32 s34, s8
	v_writelane_b32 v254, s0, 44
	s_nop 1
	v_writelane_b32 v254, s1, 45
	s_getreg_b32 s0, hwreg(HW_REG_XCC_ID, 0, 4)
	v_writelane_b32 v254, s0, 61
	s_mov_b32 s1, 0
	v_writelane_b32 v254, s1, 62
	v_writelane_b32 v254, s1, 63
	v_writelane_b32 v254, s1, 60
	s_nop 0
	v_readlane_b32 s1, v254, 0
	s_and_b32 s1, s1, 7
	s_cmp_lg_u32 s0, s1
	s_cselect_b32 s1, 0x10001, 1
	v_readlane_b32 s12, v254, 9
	v_readlane_b32 s13, v254, 10
	s_and_saveexec_b64 s[14:15], s[12:13]
	s_cbranch_execz .Lmy_xb_posted
	v_readlane_b32 s12, v254, 1
	v_readlane_b32 s13, v254, 2
	s_load_dwordx2 s[12:13], s[12:13], 0x198
	s_lshl_b32 s0, s0, 8
	s_addk_i32 s0, 0x400
	v_mov_b32_e32 v0, s0
	v_mov_b32_e32 v2, s1
	s_waitcnt lgkmcnt(0)
	global_atomic_add v0, v2, s[12:13]

; DI void grid_barrier(unsigned* bar, unsigned gen) {
;   asm volatile("s_waitcnt vmcnt(0)" ::: "memory");
;   __syncthreads();
;   if (threadIdx.x == 0) {
;     __builtin_amdgcn_fence(__ATOMIC_RELEASE, "agent");
;     const unsigned grp = blockIdx.x & 15u;
;     const unsigned nblk = (gridDim.x + 15u - grp) >> 4;
;     unsigned old = __hip_atomic_fetch_add(bar + 64 * (1 + grp), 1u, __ATOMIC_RELAXED, __HIP_MEMORY_SCOPE_AGENT);
;     if (old + 1u == nblk * gen) {
;       unsigned g = __hip_atomic_fetch_add(bar, 1u, __ATOMIC_RELAXED, __HIP_MEMORY_SCOPE_AGENT);
;       if (g + 1u == 16u * gen) {
;         for (int i = 0; i < 16; ++i) __hip_atomic_store(bar + 64 * (17 + i), gen, __ATOMIC_RELAXED, __HIP_MEMORY_SCOPE_AGENT);
;       }
;     }
;     while (__hip_atomic_load(bar + 64 * (17 + grp), __ATOMIC_RELAXED, __HIP_MEMORY_SCOPE_AGENT) < gen) __builtin_amdgcn_s_sleep(4);
;     __builtin_amdgcn_fence(__ATOMIC_ACQUIRE, "agent");
;   }
;   __syncthreads();
; }
.Lmy_xb_census:
	global_load_dword v4, v0, s[12:13] offset:0 sc1
	global_load_dword v5, v0, s[12:13] offset:256 sc1
	global_load_dword v6, v0, s[12:13] offset:512 sc1
	global_load_dword v7, v0, s[12:13] offset:768 sc1
	global_load_dword v8, v0, s[12:13] offset:1024 sc1
	global_load_dword v9, v0, s[12:13] offset:1280 sc1
	global_load_dword v10, v0, s[12:13] offset:1536 sc1
	global_load_dword v11, v0, s[12:13] offset:1792 sc1
	global_load_dword v12, v0, s[12:13] offset:2048 sc1
	global_load_dword v13, v0, s[12:13] offset:2304 sc1
	global_load_dword v14, v0, s[12:13] offset:2560 sc1
	global_load_dword v15, v0, s[12:13] offset:2816 sc1
	global_load_dword v16, v0, s[12:13] offset:3072 sc1
	global_load_dword v17, v0, s[12:13] offset:3328 sc1
	global_load_dword v18, v0, s[12:13] offset:3584 sc1
	global_load_dword v19, v0, s[12:13] offset:3840 sc1
	v_mov_b32_e32 v3, s17
	v_add_u32_e32 v3, 0x400, v3
	global_load_dword v3, v3, s[12:13] sc1
	s_waitcnt vmcnt(0)
	v_mov_b32_e32 v20, 0
	v_mov_b32_e32 v22, 0
	v_add_u32_e32 v20, v20, v4
	v_min_u32_e32 v21, 1, v4
	v_add_u32_e32 v22, v22, v21
	v_add_u32_e32 v20, v20, v5
	v_min_u32_e32 v21, 1, v5
	v_add_u32_e32 v22, v22, v21
	v_add_u32_e32 v20, v20, v6
	v_min_u32_e32 v21, 1, v6
	v_add_u32_e32 v22, v22, v21
	v_add_u32_e32 v20, v20, v7
	v_min_u32_e32 v21, 1, v7
	v_add_u32_e32 v22, v22, v21
	v_add_u32_e32 v20, v20, v8
	v_min_u32_e32 v21, 1, v8
	v_add_u32_e32 v22, v22, v21
	v_add_u32_e32 v20, v20, v9
	v_min_u32_e32 v21, 1, v9
	v_add_u32_e32 v22, v22, v21
	v_add_u32_e32 v20, v20, v10
	v_min_u32_e32 v21, 1, v10
	v_add_u32_e32 v22, v22, v21
	v_add_u32_e32 v20, v20, v11
	v_min_u32_e32 v21, 1, v11
	v_add_u32_e32 v22, v22, v21
	v_add_u32_e32 v20, v20, v12
	v_min_u32_e32 v21, 1, v12
	v_add_u32_e32 v22, v22, v21
	v_add_u32_e32 v20, v20, v13
	v_min_u32_e32 v21, 1, v13
	v_add_u32_e32 v22, v22, v21
	v_add_u32_e32 v20, v20, v14
	v_min_u32_e32 v21, 1, v14
	v_add_u32_e32 v22, v22, v21
	v_add_u32_e32 v20, v20, v15
	v_min_u32_e32 v21, 1, v15
	v_add_u32_e32 v22, v22, v21
	v_add_u32_e32 v20, v20, v16
	v_min_u32_e32 v21, 1, v16
	v_add_u32_e32 v22, v22, v21
	v_add_u32_e32 v20, v20, v17
	v_min_u32_e32 v21, 1, v17
	v_add_u32_e32 v22, v22, v21
	v_add_u32_e32 v20, v20, v18
	v_min_u32_e32 v21, 1, v18
	v_add_u32_e32 v22, v22, v21
	v_add_u32_e32 v20, v20, v19
	v_min_u32_e32 v21, 1, v19
	v_add_u32_e32 v22, v22, v21
	v_readfirstlane_b32 s18, v20
	v_readfirstlane_b32 s16, v22
	v_readfirstlane_b32 s15, v3
	v_readlane_b32 s21, v254, 32
	s_and_b32 s15, s15, 0xffff
	s_and_b32 s19, s18, 0xffff
	s_cmp_eq_u32 s19, s21
	s_cbranch_scc1 .Lmy_xb_census_done
	s_sleep 1
	s_branch .Lmy_xb_census
.Lmy_xb_census_done:
	s_lshr_b32 s18, s18, 16
	s_or_b32 s18, s18, s0
	s_xor_b32 s19, s21, 0x100
	s_or_b32 s18, s18, s19
	s_cmp_eq_u32 s18, 0
	s_cselect_b32 s23, 1, 0
	v_writelane_b32 v254, s15, 62
	v_writelane_b32 v254, s16, 63
	v_writelane_b32 v254, s23, 60
.Lmy_xb_go:
	s_nop 0
	v_readlane_b32 s23, v254, 60
	s_cmp_eq_u32 s23, 0
	s_cbranch_scc1 .Lmy_xb_glob
	s_add_i32 s18, s34, -1
	s_mul_hi_u32 s19, s18, 0x38e38e39
	s_lshr_b32 s19, s19, 1
	s_mul_i32 s21, s19, 9
	s_sub_i32 s21, s18, s21
	s_add_i32 s21, s21, -5
	s_max_i32 s21, s21, 0
	s_mul_i32 s19, s19, 3
	s_add_i32 s19, s19, s21
	s_sub_i32 s20, s20, s19
	s_cmp_gt_i32 s21, 0
	s_cbranch_scc1 .Lmy_xb_local

; DI void grid_barrier(unsigned* bar, unsigned gen) {
;   asm volatile("s_waitcnt vmcnt(0)" ::: "memory");
;   __syncthreads();
;   if (threadIdx.x == 0) {
;     __builtin_amdgcn_fence(__ATOMIC_RELEASE, "agent");
;     const unsigned grp = blockIdx.x & 15u;
;     const unsigned nblk = (gridDim.x + 15u - grp) >> 4;
;     unsigned old = __hip_atomic_fetch_add(bar + 64 * (1 + grp), 1u, __ATOMIC_RELAXED, __HIP_MEMORY_SCOPE_AGENT);
;     if (old + 1u == nblk * gen) {
;       unsigned g = __hip_atomic_fetch_add(bar, 1u, __ATOMIC_RELAXED, __HIP_MEMORY_SCOPE_AGENT);
;       if (g + 1u == 16u * gen) {
;         for (int i = 0; i < 16; ++i) __hip_atomic_store(bar + 64 * (17 + i), gen, __ATOMIC_RELAXED, __HIP_MEMORY_SCOPE_AGENT);
;       }
;     }
;     while (__hip_atomic_load(bar + 64 * (17 + grp), __ATOMIC_RELAXED, __HIP_MEMORY_SCOPE_AGENT) < gen) __builtin_amdgcn_s_sleep(4);
;     __builtin_amdgcn_fence(__ATOMIC_ACQUIRE, "agent");
;   }
;   __syncthreads();
; }
.Lmy_xb_spin_loc:
	s_sleep 1
	global_load_dword v3, v0, s[12:13] sc1
	s_waitcnt vmcnt(0)
	v_readfirstlane_b32 s18, v3
	s_cmp_lt_u32 s18, s20
	s_cbranch_scc1 .Lmy_xb_spin_loc
	buffer_inv sc1
	s_waitcnt vmcnt(0)
	s_branch .LBB0_28
.Lmy_xb_local:
	v_mov_b32_e32 v0, s17
	v_add_u32_e32 v0, 0x1480, v0
	global_atomic_add v3, v0, v2, s[12:13] sc0
	v_mov_b32_e32 v4, s17
	v_add_u32_e32 v4, 0x2480, v4
	s_mul_i32 s21, s19, s15
	s_waitcnt vmcnt(0)
	v_readfirstlane_b32 s18, v3
	s_add_i32 s18, s18, 1
	s_cmp_eq_u32 s18, s21
	s_cbranch_scc0 .Lmy_xb_lspin
	global_atomic_add v4, v2, s[12:13]
	s_branch .Lmy_xb_lacq
.Lmy_xb_lspin:
	s_sleep 1
	global_load_dword v3, v4, s[12:13] sc1
	s_waitcnt vmcnt(0)
	v_readfirstlane_b32 s18, v3
	s_cmp_lt_u32 s18, s19
	s_cbranch_scc1 .Lmy_xb_lspin
.Lmy_xb_lacq:
	buffer_inv sc1
	s_waitcnt vmcnt(0)
